# split cg grid.sync into arrive at top + wait after P0 prologue (hides sync latency behind P0)
# speedup vs baseline: 1.0041x; 1.0041x over previous
; #define LAS __attribute__((address_space(3)))
; __global__ void __launch_bounds__(512, 2) layer_fwd(Args args) {
;     ...
;     if (F.tid < 64) ((LAS unsigned*)(F.lds + LDSCTL_OFF))[F.tid] = 0u;
;     __syncthreads();
;     ...
;     static_assert(GSYNC_SEAM == -1, "the executed grid.sync() is the one below");
;     if (F.bid == 0) { unsigned* bz = (unsigned*)(ws + WS_CTL) + 4096;
; #pragma unroll
;         for (int i = 0; i < 8; ++i) bz[F.tid + 512 * i] = 0u; }
;     cg::this_grid().sync();
.LBB0_4:
	s_load_dwordx2 s[82:83], s[0:1], 0xb8
	s_load_dwordx2 s[96:97], s[6:7], 0x4
	v_lshrrev_b32_e32 v1, 20, v0
	v_lshrrev_b32_e32 v0, 10, v0
	v_or_b32_e32 v0, v0, v1
	s_movk_i32 s3, 0x3ff
	v_and_or_b32 v0, v0, s3, v228
	v_cmp_eq_u32_e32 vcc, 0, v0
	s_waitcnt vmcnt(0) lgkmcnt(0)
	s_barrier
	s_and_saveexec_b64 s[4:5], vcc
	s_cbranch_execz .LBB0_14
	buffer_wbl2 sc1
	s_waitcnt vmcnt(0)
	s_load_dwordx2 s[6:7], s[6:7], 0x58
	v_mov_b32_e32 v2, 0
	s_mov_b64 s[8:9], exec
	v_mbcnt_lo_u32_b32 v1, s8, 0
	v_mbcnt_hi_u32_b32 v1, s9, v1
	s_waitcnt lgkmcnt(0)
	global_load_dword v0, v2, s[6:7] offset:40
	v_cmp_eq_u32_e32 vcc, 0, v1
	s_and_saveexec_b64 s[12:13], vcc
	s_cbranch_execz .LBB0_7
	s_bcnt1_i32_b64 s3, s[8:9]
	v_mov_b32_e32 v3, s3
	global_atomic_add v3, v2, v3, s[6:7] offset:32 sc0

; #define LAS __attribute__((address_space(3)))
; __device__ __forceinline__ void transpose_items(Frame& F, int it0, int it1, int gw, int NGW) {
;     LAS float* scr = (LAS float*)(F.lds + F.wave * 16384);
;     bf16_t* Win_t = (bf16_t*)(F.ws + WS_WIN); bf16_t* Wout_t = (bf16_t*)(F.ws + WS_WOUT); bf16_t* Wq_t = (bf16_t*)(F.ws + WS_WQ); bf16_t* Wkv_t = (bf16_t*)(F.ws + WS_WKV);
;     bf16_t* Wo_t = (bf16_t*)(F.ws + WS_WO); bf16_t* Wup_t = (bf16_t*)(F.ws + WS_WUP); bf16_t* Wdn_t = (bf16_t*)(F.ws + WS_WDN);
;     for (int it = it0 + gw; it < it1; it += NGW) {
;         int r = it;
;         if (r < I_IN) { const int kb = r / 88, nb = r % 88; p0_transpose_item(F.w_in, D, INW, Win_t, win_dest(32 * nb), nullptr, scr, 64 * kb, 32 * nb, F.lane); continue; } r -= I_IN;
;         if (r < I_KV) { const int kb = r / 32, nb = r % 32; p0_transpose_item(F.wkv, D, D, Wkv_t, 32 * nb, nullptr, scr, 64 * kb, 32 * nb, F.lane); continue; } r -= I_KV;
; __global__ void __launch_bounds__(512, 2) layer_fwd(Args args) {
;     ...
;     F.x = (const float*)args.in[0]; F.mem = (const float*)args.in[1]; F.pos = (const int*)args.in[2]; F.g1 = (const float*)args.in[3]; F.w_in = (const float*)args.in[4];
;     F.hlb = (const float*)args.in[5]; F.hng = (const float*)args.in[6]; F.qng = (const float*)args.in[7]; F.kng = (const float*)args.in[8]; F.sinks = (const float*)args.in[9];
;     F.w_out = (const float*)args.in[10]; F.g2 = (const float*)args.in[11]; F.gm = (const float*)args.in[12]; F.wq = (const float*)args.in[13]; F.wkv = (const float*)args.in[14];
;     F.xqg = (const float*)args.in[15]; F.xkg = (const float*)args.in[16]; F.wo = (const float*)args.in[17]; F.g3 = (const float*)args.in[18]; F.wup = (const float*)args.in[19]; F.wdn = (const float*)args.in[20];
;     F.out = args.out; F.ws = args.ws;
;     unsigned char* ws = args.ws;
;     const int lo = args.ph_lo, hi = args.ph_hi;
;     ...
;     if (F.tid < 64) ((LAS unsigned*)(F.lds + LDSCTL_OFF))[F.tid] = 0u;
;     __syncthreads();
;     ...
;     static_assert(GSYNC_SEAM == -1, "the executed grid.sync() is the one below");
;     if (F.bid == 0) { unsigned* bz = (unsigned*)(ws + WS_CTL) + 4096;
; #pragma unroll
;         for (int i = 0; i < 8; ++i) bz[F.tid + 512 * i] = 0u; }
;     cg::this_grid().sync();
;     XcdBarrier xbar = xcd_barrier_post((unsigned*)(ws + WS_CTL) + 4096, (volatile LAS unsigned*)(F.lds + LDSCTL_OFF) + 8);
.LBB0_10:
	s_or_b64 exec, exec, s[8:9]
	v_and_b32_e32 v1, 0xffff0000, v1
	v_mov_b32_e32 v0, 0x25040
	v_mov_b32_e32 v2, s6
	v_mov_b32_e32 v3, s7
	ds_write_b32 v0, v1
	ds_write_b32 v0, v2 offset:4
	ds_write_b32 v0, v3 offset:8
	s_waitcnt lgkmcnt(0)
.LBB0_14:
	s_or_b64 exec, exec, s[4:5]
	s_load_dwordx16 s[12:27], s[0:1], 0x0
	s_barrier
	s_waitcnt lgkmcnt(0)
	s_add_u32 s94, s92, 0x4000
	s_addc_u32 s95, s93, 0
	v_writelane_b32 v254, s12, 8
	v_cmp_eq_u32_e64 s[50:51], 0, v228
	s_nop 0
	v_writelane_b32 v254, s13, 9
	v_writelane_b32 v254, s14, 10
	v_writelane_b32 v254, s15, 11
	v_writelane_b32 v254, s16, 12
	v_writelane_b32 v254, s17, 13
	v_writelane_b32 v254, s18, 14
	v_writelane_b32 v254, s19, 15
	v_writelane_b32 v254, s20, 16
	v_writelane_b32 v254, s21, 17
	v_writelane_b32 v254, s22, 18
	v_writelane_b32 v254, s23, 19
	v_writelane_b32 v254, s24, 20
	v_writelane_b32 v254, s25, 21
	v_writelane_b32 v254, s26, 22
	v_writelane_b32 v254, s27, 23
	s_load_dwordx16 s[12:27], s[0:1], 0x40
	s_getreg_b32 s0, hwreg(HW_REG_XCC_ID, 0, 4)
	s_and_b32 s85, s0, 15
	s_waitcnt lgkmcnt(0)
	v_writelane_b32 v254, s12, 24
	s_nop 1
	v_writelane_b32 v254, s13, 25
	v_writelane_b32 v254, s14, 26
	v_writelane_b32 v254, s15, 27
	v_writelane_b32 v254, s16, 28
	v_writelane_b32 v254, s17, 29
	v_writelane_b32 v254, s18, 30
	v_writelane_b32 v254, s19, 31
	v_writelane_b32 v254, s20, 32
	v_writelane_b32 v254, s21, 33
	v_writelane_b32 v254, s22, 34
	v_writelane_b32 v254, s23, 35
	v_writelane_b32 v254, s24, 36
	v_writelane_b32 v254, s25, 37
	v_writelane_b32 v254, s26, 38
	v_writelane_b32 v254, s27, 39
	s_lshr_b32 s3, s68, 6
	s_add_u32 s0, s92, 0x100000
	s_addc_u32 s1, s93, 0
	s_cmp_lt_i32 s82, 1
	s_cselect_b64 s[4:5], -1, 0
	s_cmp_gt_i32 s83, 0
	s_cselect_b64 s[6:7], -1, 0
	v_writelane_b32 v254, s0, 40
	s_and_b64 s[12:13], s[4:5], s[6:7]
	s_andn2_b64 vcc, exec, s[12:13]
	v_writelane_b32 v254, s1, 41
	v_and_b32_e32 v208, 63, v228
	s_cbranch_vccnz .LBB0_96
	s_lshl_b32 s4, s2, 3
	s_add_i32 s14, s3, s4
	s_lshl_b32 s30, s33, 3
	s_cmpk_gt_i32 s33, 0x7f
	s_movk_i32 s4, 0x780
	s_cselect_b32 s15, s4, 0x1b80
	s_cmp_ge_i32 s14, s15
	s_cbranch_scc1 .LBB0_60
	s_lshl_b32 s4, s3, 14
	v_lshrrev_b32_e32 v62, 5, v208
	v_and_b32_e32 v0, 31, v228
	s_add_i32 s4, s4, 0
	v_lshlrev_b32_e32 v0, 2, v0
	v_mul_u32_u24_e32 v4, 0x84, v62
	v_add3_u32 v63, s4, v0, v4
	v_lshlrev_b32_e32 v4, 3, v228
	v_mov_b32_e32 v1, 0
	v_and_b32_e32 v4, 56, v4
	v_readlane_b32 s16, v254, 0
	v_mul_u32_u24_e32 v6, 0x84, v4
	v_lshlrev_b32_e32 v4, 1, v4
	v_mov_b32_e32 v5, v1
	v_readlane_b32 s17, v254, 1
	v_lshl_add_u64 v[28:29], s[92:93], 0, v[4:5]
	v_readlane_b32 s20, v254, 4
	v_readlane_b32 s21, v254, 5
	v_readlane_b32 s52, v254, 24
	s_mov_b64 s[16:17], 0x980000
	s_mov_b64 s[6:7], 0x1580000
	s_cmp_lg_u64 s[20:21], 0
	v_readlane_b32 s53, v254, 25
	v_readlane_b32 s54, v254, 26
	v_readlane_b32 s55, v254, 27
	v_readlane_b32 s56, v254, 28
	v_readlane_b32 s57, v254, 29
	v_readlane_b32 s58, v254, 30
	v_readlane_b32 s59, v254, 31
	v_readlane_b32 s60, v254, 32
	v_readlane_b32 s61, v254, 33
	v_readlane_b32 s62, v254, 34
	v_readlane_b32 s63, v254, 35
	v_readlane_b32 s64, v254, 36
	v_readlane_b32 s65, v254, 37
	v_readlane_b32 s66, v254, 38
	v_readlane_b32 s67, v254, 39
	v_lshl_add_u64 v[16:17], v[28:29], 0, s[16:17]
	s_mov_b64 s[16:17], 0x780000
	v_lshrrev_b32_e32 v64, 3, v208
	v_lshl_add_u64 v[4:5], v[28:29], 0, s[6:7]
	s_cselect_b64 s[6:7], -1, 0
	s_mov_b64 s[8:9], 0xd80000
	v_lshl_add_u64 v[14:15], s[62:63], 0, v[0:1]
	s_cmp_lg_u64 s[58:59], 0
	v_lshl_add_u64 v[18:19], s[56:57], 0, v[0:1]
	v_lshl_add_u64 v[20:21], v[28:29], 0, s[16:17]
	v_lshl_add_u64 v[22:23], s[64:65], 0, v[0:1]
	s_mov_b64 s[16:17], 0xa80000
	v_readlane_b32 s52, v254, 8
	v_lshlrev_b32_e32 v7, 2, v64
	v_readlane_b32 s18, v254, 2
	v_readlane_b32 s19, v254, 3
	v_readlane_b32 s22, v254, 6
	v_readlane_b32 s23, v254, 7
	v_lshl_add_u64 v[8:9], v[28:29], 0, s[8:9]
	s_mov_b64 s[8:9], 0xc80000
	v_lshl_add_u64 v[24:25], v[28:29], 0, s[16:17]
	v_readlane_b32 s60, v254, 16
	v_readlane_b32 s61, v254, 17
	s_mov_b64 s[16:17], 0x200000
	s_mov_b32 s5, 0
	v_lshl_add_u64 v[2:3], s[88:89], 0, v[0:1]
	v_add3_u32 v65, s4, v6, v7
	v_or_b32_e32 v66, 8, v64
	v_or_b32_e32 v67, 16, v64
	v_or_b32_e32 v68, 24, v64
	v_lshl_add_u64 v[6:7], s[22:23], 0, v[0:1]
	v_lshl_add_u64 v[10:11], s[18:19], 0, v[0:1]
	v_lshl_add_u64 v[12:13], v[28:29], 0, s[8:9]
	s_cselect_b64 s[8:9], -1, 0
	v_lshl_add_u64 v[26:27], s[60:61], 0, v[0:1]
	v_lshl_add_u64 v[28:29], v[28:29], 0, s[16:17]
	s_lshl_b32 s20, s14, 5
	s_lshl_b32 s21, s30, 5
	s_lshl_b32 s22, s14, 6
	s_lshl_b32 s23, s30, 6
	s_lshl_b32 s24, s14, 1
	s_lshl_b32 s25, s30, 1
	s_lshl_b32 s26, s14, 2
	s_lshl_b32 s27, s30, 2
	s_movk_i32 s28, 0x7fff
	s_mov_b32 s29, 0xffff0000
	s_movk_i32 s31, 0x2c00
	v_add_u32_e32 v69, 0x400, v63
	v_add_u32_e32 v70, 0x800, v63
	v_add_u32_e32 v71, 0xc00, v63
	v_add_u32_e32 v72, 0x1000, v63
	v_add_u32_e32 v73, 0x1400, v63
	v_add_u32_e32 v74, 0x1800, v63
	v_add_u32_e32 v75, 0x1c00, v63
	v_mov_b32_e32 v76, 0xa00
	s_mov_b32 s34, s14
	v_readlane_b32 s53, v254, 9
	v_readlane_b32 s54, v254, 10
	v_readlane_b32 s55, v254, 11
	v_readlane_b32 s56, v254, 12
	v_readlane_b32 s57, v254, 13
	v_readlane_b32 s58, v254, 14
	v_readlane_b32 s59, v254, 15
	v_readlane_b32 s62, v254, 18
	v_readlane_b32 s63, v254, 19
	v_readlane_b32 s64, v254, 20
	v_readlane_b32 s65, v254, 21
	v_readlane_b32 s66, v254, 22
	v_readlane_b32 s67, v254, 23
	s_branch .LBB0_23

; __device__ __forceinline__ unsigned xb_ld(unsigned* p)              { return __hip_atomic_load(p, __ATOMIC_RELAXED, __HIP_MEMORY_SCOPE_AGENT); }
; __device__ __forceinline__ unsigned xb_add(unsigned* p, unsigned v) { return __hip_atomic_fetch_add(p, v, __ATOMIC_RELAXED, __HIP_MEMORY_SCOPE_AGENT); }
; __device__ __forceinline__ void xcd_barrier_complete(unsigned* bar, unsigned x, unsigned& nloc, unsigned& nx) {
;     const unsigned G = gridDim.x * gridDim.y * gridDim.z;
;     unsigned sum, cnt, mine, sp = 0u;
;     for (;;) {
;         sum = 0u; cnt = 0u; mine = 0u;
; #pragma unroll
;         for (unsigned j = 0; j < 16; ++j) { const unsigned c = xb_ld(&bar[XB_XCNT(j)]); sum += c; cnt += (c > 0u) ? 1u : 0u; mine = (j == x) ? c : mine; }
;         if (sum == G) break;
; __device__ __forceinline__ void xcd_barrier(const XcdBarrier& b) {
;     asm volatile("s_waitcnt vmcnt(0)" ::: "memory");
;     __syncthreads();
;     if (threadIdx.x == 0) {
;         unsigned* bar = b.bar;
;         __builtin_amdgcn_s_waitcnt(0);
;         unsigned nloc = b.st[0], nx = b.st[1];
;         if (nloc == 0u) { xcd_barrier_complete(bar, b.x, nloc, nx); b.st[0] = nloc; b.st[1] = nx; }
;         const unsigned old = xb_add(&bar[XB_XSUB(b.x)], 1u);
;         const unsigned gen = old / nloc;
;         if (old + 1u == (gen + 1u) * nloc) {
.LBB0_96:
	s_cmp_gt_i32 s83, 1
	s_cselect_b64 s[4:5], -1, 0
	s_and_b64 s[6:7], s[12:13], s[4:5]
	s_andn2_b64 vcc, exec, s[6:7]
	s_cbranch_vccnz .LBB0_150
	s_waitcnt vmcnt(0)
	s_waitcnt lgkmcnt(0)
	s_barrier
	s_and_saveexec_b64 s[6:7], s[50:51]
	s_cbranch_execz .LBB0_149
	v_mov_b32_e32 v0, 0x25040
	ds_read_b32 v1, v0
	ds_read_b32 v2, v0 offset:4
	ds_read_b32 v3, v0 offset:8
	s_waitcnt lgkmcnt(0)
	v_readfirstlane_b32 s8, v2
	v_readfirstlane_b32 s9, v3
	v_mov_b32_e32 v0, 0
	s_nop 4
.Lcgw_spin:
	global_load_dword v2, v0, s[8:9] offset:32 sc1
	s_waitcnt vmcnt(0)
	v_and_b32_e32 v2, 0xffff0000, v2
	v_cmp_ne_u32_e32 vcc, v2, v1
	s_cbranch_vccnz .Lcgw_done
	s_sleep 1
	s_branch .Lcgw_spin
.Lcgw_done:
	s_lshl_b32 s10, s85, 8
	v_mov_b32_e32 v1, s10
	v_mov_b32_e32 v2, 1
	global_atomic_add v1, v1, v2, s[94:95] offset:1024 sc0
	v_mov_b32_e32 v0, 0x25028
	s_waitcnt vmcnt(0)
	ds_write_b32 v0, v1
	s_add_i32 s8, 0, 0x25020
	v_mov_b32_e32 v0, s8
	s_waitcnt vmcnt(0) expcnt(0) lgkmcnt(0)
	ds_read_b32 v2, v0
	s_add_i32 s8, 0, 0x25024
	v_mov_b32_e32 v0, s8
	ds_read_b32 v0, v0
	s_waitcnt lgkmcnt(1)
	v_cmp_ne_u32_e32 vcc, 0, v2
	s_cbranch_vccnz .LBB0_113
	s_add_u32 s8, s92, 0x4200
	s_addc_u32 s9, s93, 0
	s_add_u32 s10, s92, 0x4400
	s_addc_u32 s11, s93, 0
	s_add_u32 s12, s92, 0x4500
	s_addc_u32 s13, s93, 0
	s_add_u32 s14, s92, 0x4600
	s_addc_u32 s15, s93, 0
	s_add_u32 s16, s92, 0x4700
	s_addc_u32 s17, s93, 0
	s_add_u32 s18, s92, 0x4800
	s_addc_u32 s19, s93, 0
	s_add_u32 s20, s92, 0x4900
	s_addc_u32 s21, s93, 0
	s_add_u32 s22, s92, 0x4a00
	s_addc_u32 s23, s93, 0
	s_add_u32 s24, s92, 0x4b00
	s_addc_u32 s25, s93, 0
	s_add_u32 s26, s92, 0x4c00
	s_addc_u32 s27, s93, 0
	s_add_u32 s28, s92, 0x4d00
	s_addc_u32 s29, s93, 0
	s_add_u32 s30, s92, 0x4e00
	s_addc_u32 s31, s93, 0
	s_add_u32 s34, s92, 0x4f00
	s_addc_u32 s35, s93, 0
	s_add_u32 s36, s92, 0x5000
	s_addc_u32 s37, s93, 0
	s_add_u32 s38, s92, 0x5100
	s_addc_u32 s39, s93, 0
	s_add_u32 s40, s92, 0x5200
	s_addc_u32 s41, s93, 0
	s_mul_i32 s48, s97, s33
	s_add_u32 s42, s92, 0x5300
	s_mul_i32 s48, s48, s96
	s_addc_u32 s43, s93, 0
	s_mov_b32 s49, 1
	v_mov_b32_e32 v16, 0
	s_branch .LBB0_101
